# residual (EpiResid) epilogue software-pipelined: 16 row-quad loads in flight, counted vmcnt, store as each fma completes (paired re-test on the current best)
# baseline (speedup 1.0000x reference)
.Lpost_514:
	s_min_i32 s2, s85, 0x80
	s_ashr_i32 s2, s2, 4
	s_lshl_b32 s84, s85, 8
	s_mul_hi_i32 s3, s2, 0x9000
	s_mul_i32 s2, s2, 0x9000
	s_add_u32 s2, s42, s2
	v_lshl_or_b32 v144, s24, 8, v213
	s_addc_u32 s3, s43, s3
	v_ashrrev_i32_e32 v145, 31, v144
	v_lshl_add_u64 v[140:141], v[144:145], 2, s[2:3]
	global_load_dwordx4 v[128:131], v[140:141], off
	global_load_dwordx4 v[132:135], v[140:141], off offset:64
	global_load_dwordx4 v[136:139], v[140:141], off offset:512
	s_nop 0
	global_load_dwordx4 v[140:143], v[140:141], off offset:576
	v_lshl_add_u64 v[170:171], v[164:165], 0, v[144:145]
	s_cmpk_lt_i32 s85, 0x80
	s_mov_b64 s[2:3], -1
	s_cbranch_scc1 .Lres_lat
	s_waitcnt vmcnt(0)
	v_pk_mul_f32 v[184:185], s[68:69], v[130:131]
	v_pk_mul_f32 v[186:187], s[46:47], v[128:129]
	v_pk_mul_f32 v[180:181], s[68:69], v[134:135]
	v_pk_mul_f32 v[182:183], s[46:47], v[132:133]
	v_pk_mul_f32 v[176:177], s[68:69], v[138:139]
	v_pk_mul_f32 v[178:179], s[46:47], v[136:137]
	v_pk_mul_f32 v[172:173], s[68:69], v[142:143]
	v_pk_mul_f32 v[174:175], s[46:47], v[140:141]
	s_branch .LBB0_517
